# scan S3: move the H waves' KT*v state-update MFMAs (independent of the solve) out of critical S3 into their S2 slack
# speedup vs baseline: 1.0067x; 1.0041x over previous
; #define LAS __attribute__((address_space(3)))
; #define MFMA32(a, b, c) __builtin_amdgcn_mfma_f32_32x32x16_bf16((a), (b), (c), 0, 0, 0)
; __device__ __forceinline__ void scan_pass1(const ScanP& sp, int b, int h, int seg, LAS unsigned char* lds) {
;     ...
;         if (w < 4) {
; #pragma unroll
;             for (int i = 0; i < 16; ++i) { P1[i] = 0.f; P2[i] = 0.f; }
; #pragma unroll
;             for (int jb = 0; jb < 2; ++jb)
; #pragma unroll
;                 for (int s = 0; s < 2; ++s) {
;                     const bf16x8 hb = pack8(Hacc[jb], s);
;                     const int off = (ln * 72 + 32 * jb + 16 * s + 4 * hh) * 2;
;                     P1 = MFMA32(ld_krow(lds + O_KK + off), hb, P1);
;                     P2 = MFMA32(ld_krow(lds + O_R + off), hb, P2);
;                 }
;     ...
;             for (int jb = 0; jb < 2; ++jb) {
;                 if (isH) {
; #pragma unroll
;                     for (int ks = 0; ks < 2; ++ks) Hacc[jb] = MFMA32(*(const LAS bf16x8*)(lds + O_KT + ((32 * jb + ln) * 40 + ks * 16 + hh * 8) * 2), vfr[ks], Hacc[jb]);
;                 }
.LBB0_284:
	s_andn2_b64 vcc, exec, s[0:1]
	s_cbranch_vccnz .LBB0_286
	v_lshlrev_b32_e32 v2, 3, v188
	v_add3_u32 v0, v2, v0, 0
	v_add_u32_e32 v2, 0x8000, v0
	v_add_u32_e32 v0, 0x9000, v0
	ds_read2_b64 v[36:39], v2 offset1:2
	ds_read2_b64 v[68:71], v2 offset0:4 offset1:6
	ds_read2_b64 v[56:59], v0 offset0:64 offset1:66
	ds_read2_b64 v[230:233], v0 offset0:68 offset1:70
	ds_read2_b64 v[234:237], v2 offset0:8 offset1:10
	ds_read2_b64 v[238:241], v0 offset0:72 offset1:74
	ds_read2_b64 v[242:245], v2 offset0:12 offset1:14
	ds_read2_b64 v[246:249], v0 offset0:76 offset1:78
	v_cvt_pk_bf16_f32 v52, v20, v21
	v_cvt_pk_bf16_f32 v53, v22, v23
	v_cvt_pk_bf16_f32 v54, v24, v25
	v_cvt_pk_bf16_f32 v55, v26, v27
	v_cvt_pk_bf16_f32 v72, v28, v29
	v_cvt_pk_bf16_f32 v73, v30, v31
	v_cvt_pk_bf16_f32 v74, v32, v33
	v_cvt_pk_bf16_f32 v75, v34, v35
	s_waitcnt lgkmcnt(7)
	s_nop 0
	v_mfma_f32_32x32x16_bf16 v[36:51], v[36:39], v[52:55], 0
	s_waitcnt lgkmcnt(6)
	v_mfma_f32_32x32x16_bf16 v[36:51], v[68:71], v[72:75], v[36:51]
	s_waitcnt lgkmcnt(5)
	v_mfma_f32_32x32x16_bf16 v[52:67], v[56:59], v[52:55], 0
	s_waitcnt lgkmcnt(4)
	v_mfma_f32_32x32x16_bf16 v[52:67], v[230:233], v[72:75], v[52:67]
	s_nop 1
	v_cvt_pk_bf16_f32 v72, v4, v5
	v_cvt_pk_bf16_f32 v73, v6, v7
	v_cvt_pk_bf16_f32 v74, v8, v9
	v_cvt_pk_bf16_f32 v75, v10, v11
	s_waitcnt lgkmcnt(3)
	s_nop 1
	v_mfma_f32_32x32x16_bf16 v[36:51], v[234:237], v[72:75], v[36:51]
	s_waitcnt lgkmcnt(2)
	v_mfma_f32_32x32x16_bf16 v[52:67], v[238:241], v[72:75], v[52:67]
	s_nop 1
	v_cvt_pk_bf16_f32 v72, v12, v13
	v_cvt_pk_bf16_f32 v73, v14, v15
	v_cvt_pk_bf16_f32 v74, v16, v17
	v_cvt_pk_bf16_f32 v75, v18, v19
	s_waitcnt lgkmcnt(1)
	s_nop 1
	v_mfma_f32_32x32x16_bf16 v[36:51], v[242:245], v[72:75], v[36:51]
	s_waitcnt lgkmcnt(0)
	v_mfma_f32_32x32x16_bf16 v[52:67], v[246:249], v[72:75], v[52:67]
	s_andn2_b64 vcc, exec, s[54:55]
	s_cbranch_vccnz .Lkt_skip
	v_or_b32_e32 v230, s82, v189
	v_mul_u32_u24_e32 v231, 0x50, v189
	v_lshlrev_b32_e32 v232, 4, v188
	v_mul_u32_u24_e32 v230, 0x50, v230
	v_add_u32_e32 v68, v231, v232
	v_add_u32_e32 v69, v230, v232
	ds_read_b128 v[230:233], v69 offset:61440
	ds_read_b128 v[238:241], v68 offset:51200
	ds_read_b128 v[246:249], v68 offset:53760
	ds_read_b128 v[234:237], v69 offset:61472
	ds_read_b128 v[242:245], v68 offset:51232
	ds_read_b128 v[68:71], v68 offset:53792
	s_waitcnt lgkmcnt(4)
	v_mfma_f32_32x32x16_bf16 v[20:35], v[238:241], v[230:233], v[20:35]
	s_waitcnt lgkmcnt(3)
	v_mfma_f32_32x32x16_bf16 v[4:19], v[246:249], v[230:233], v[4:19]
	s_waitcnt lgkmcnt(1)
	v_mfma_f32_32x32x16_bf16 v[20:35], v[242:245], v[234:237], v[20:35]
	s_waitcnt lgkmcnt(0)
	v_mfma_f32_32x32x16_bf16 v[4:19], v[68:71], v[234:237], v[4:19]
.Lkt_skip:
.LBB0_286:
	s_add_i32 s22, s83, 1
	s_cmp_eq_u32 s83, 31
	s_cbranch_scc1 .LBB0_300
	ds_read_b128 v[68:71], v167
	s_waitcnt lgkmcnt(0)
	v_sub_f32_e32 v73, v89, v85
	v_sub_f32_e32 v72, v88, v84
	v_sub_f32_e32 v3, v91, v87
	v_sub_f32_e32 v2, v90, v86
	v_pk_fma_f32 v[2:3], v[2:3], v[70:71], v[86:87]
	v_pk_fma_f32 v[68:69], v[72:73], v[68:69], v[84:85]
	s_and_saveexec_b64 s[0:1], s[6:7]
	s_cbranch_execz .LBB0_289
	v_add_f32_e32 v0, v68, v68
	v_mul_f32_e32 v0, 0x3fb8aa3b, v0
	v_exp_f32_e32 v0, v0
	v_add_f32_e32 v68, v69, v69
	v_mul_f32_e32 v68, 0x3fb8aa3b, v68
	v_exp_f32_e32 v69, v68
	v_add_f32_e32 v0, 1.0, v0
	v_rcp_f32_e32 v68, v0
	v_add_f32_e32 v0, v2, v2
	v_mul_f32_e32 v0, 0x3fb8aa3b, v0
	v_add_f32_e32 v2, v3, v3
	v_exp_f32_e32 v0, v0
	v_mul_f32_e32 v2, 0x3fb8aa3b, v2
	v_exp_f32_e32 v3, v2
	v_add_f32_e32 v69, 1.0, v69
	v_add_f32_e32 v0, 1.0, v0
	v_rcp_f32_e32 v2, v0
	v_add_f32_e32 v0, 1.0, v3
	v_rcp_f32_e32 v3, v0
	v_rcp_f32_e32 v69, v69
	v_pk_fma_f32 v[2:3], v[2:3], -2.0, 1.0 op_sel_hi:[1,0,0]
	v_pk_fma_f32 v[68:69], v[68:69], -2.0, 1.0 op_sel_hi:[1,0,0]

; #define LAS __attribute__((address_space(3)))
; #define MFMA32(a, b, c) __builtin_amdgcn_mfma_f32_32x32x16_bf16((a), (b), (c), 0, 0, 0)
; __device__ __forceinline__ int crow(int r, int hi) { return (r & 3) + 8 * (r >> 2) + 4 * hi; }
; __device__ __forceinline__ void scan_pass1(const ScanP& sp, int b, int h, int seg, LAS unsigned char* lds) {
;     ...
;             f32x16 Aa;
; #pragma unroll
;             for (int i = 0; i < 16; ++i) Aa[i] = 0.f;
; #pragma unroll
;             for (int s = 0; s < 1; ++s) Aa = MFMA32(ld_krow(lds + O_TM + (ln * 40 + 4 * hh) * 2), pack8(P1, 0), Aa);
;             P1 = MFMA32(ld_krow(lds + O_N21 + (ln * 40 + 4 * hh) * 2), pack8(Aa, 0), P1);
;             Aa = MFMA32(ld_krow(lds + O_TM + (ln * 40 + 16 + 4 * hh) * 2), pack8(P1, 1), Aa);
;             bf16x8 ab[2]; ab[0] = pack8(Aa, 0); ab[1] = pack8(Aa, 1);
; #pragma unroll
;             for (int s = 0; s < 2; ++s) P2 = MFMA32(ld_krow(lds + O_NB + (ln * 40 + 16 * s + 4 * hh) * 2), ab[s], P2);
; #pragma unroll
;             for (int jb = 0; jb < 2; ++jb) {
;                 if (isH) {
; #pragma unroll
;                     for (int ks = 0; ks < 2; ++ks) Hacc[jb] = MFMA32(*(const LAS bf16x8*)(lds + O_KT + ((32 * jb + ln) * 40 + ks * 16 + hh * 8) * 2), vfr[ks], Hacc[jb]);
;                 }
; #pragma unroll
;                 for (int s = 0; s < 2; ++s) Hacc[jb] = MFMA32(ld_krow(lds + O_BT + ((32 * jb + ln) * 40 + 16 * s + 4 * hh) * 2), ab[s], Hacc[jb]);
; #pragma unroll
;                 for (int g = 0; g < 4; ++g) {
;                     const f32x4 gv = *(const LAS f32x4*)(gam + 32 * jb + 8 * g + 4 * hh);
;                     Hacc[jb][4 * g] *= gv[0]; Hacc[jb][4 * g + 1] *= gv[1]; Hacc[jb][4 * g + 2] *= gv[2]; Hacc[jb][4 * g + 3] *= gv[3];
;                 }
;             }
;             LAS float* ob = isH ? yb : qb;
; #pragma unroll
;             for (int r = 0; r < 16; ++r) ob[crow(r, hh) * 64 + icol] = P2[r];
.LBB0_310:
	v_lshlrev_b32_e32 v68, 3, v188
	s_add_i32 s0, 0, 0x11800
	v_add3_u32 v68, s0, v68, v112
	ds_read2_b64 v[68:71], v68 offset1:2
	v_lshlrev_b32_e32 v115, 2, v188
	v_mad_u32_u24 v123, v189, 40, v115
	v_lshlrev_b32_e32 v116, 1, v123
	v_add_u32_e32 v114, 0, v116
	v_cvt_pk_bf16_f32 v72, v36, v37
	v_cvt_pk_bf16_f32 v73, v38, v39
	v_cvt_pk_bf16_f32 v74, v40, v41
	v_cvt_pk_bf16_f32 v75, v42, v43
	v_add_u32_e32 v104, 0x1aa00, v114
	ds_read2_b64 v[104:107], v104 offset1:2
	s_waitcnt lgkmcnt(0)
	v_mfma_f32_32x32x16_bf16 v[68:83], v[68:71], v[72:75], 0
	v_add_u32_e32 v139, 0, v113
	v_cndmask_b32_e64 v113, 0, 1, s[54:55]
	s_andn2_b64 vcc, exec, s[54:55]
	s_nop 8
	v_cvt_pk_bf16_f32 v108, v68, v69
	v_cvt_pk_bf16_f32 v109, v70, v71
	v_cvt_pk_bf16_f32 v110, v72, v73
	v_cvt_pk_bf16_f32 v111, v74, v75
	s_nop 1
	v_mfma_f32_32x32x16_bf16 v[36:51], v[104:107], v[108:111], v[36:51]
	v_add_u32_e32 v104, s0, v116
	ds_read2_b64 v[104:107], v104 offset0:4 offset1:6
	v_cmp_ne_u32_e64 s[0:1], 1, v113
	s_nop 8
	v_cvt_pk_bf16_f32 v108, v44, v45
	v_cvt_pk_bf16_f32 v109, v46, v47
	v_cvt_pk_bf16_f32 v110, v48, v49
	v_cvt_pk_bf16_f32 v111, v50, v51
	s_waitcnt lgkmcnt(0)
	s_nop 0
	v_mfma_f32_32x32x16_bf16 v[68:83], v[104:107], v[108:111], v[68:83]
	v_add_u32_e32 v104, 0x12200, v114
	v_add_u32_e32 v108, 0x12220, v114
	ds_read2_b64 v[104:107], v104 offset1:2
	ds_read2_b64 v[108:111], v108 offset1:2
.LBB0_312:
	v_cvt_pk_bf16_f32 v68, v68, v69
	v_cvt_pk_bf16_f32 v69, v70, v71
	v_cvt_pk_bf16_f32 v70, v72, v73
	v_cvt_pk_bf16_f32 v71, v74, v75
	v_cvt_pk_bf16_f32 v72, v76, v77
	v_cvt_pk_bf16_f32 v74, v80, v81
	v_lshl_add_u32 v76, v115, 2, 0
	v_add_u32_e32 v80, 0xd800, v114
	v_cvt_pk_bf16_f32 v73, v78, v79
	v_cvt_pk_bf16_f32 v75, v82, v83
	v_add_u32_e32 v138, 0x13c00, v76
	ds_read2_b64 v[76:79], v80 offset0:128 offset1:130
	ds_read2_b64 v[80:83], v80 offset0:132 offset1:134
	s_waitcnt lgkmcnt(0)
	v_mfma_f32_32x32x16_bf16 v[20:35], v[76:79], v[68:71], v[20:35]
	s_and_b64 vcc, exec, s[0:1]
	v_mfma_f32_32x32x16_bf16 v[20:35], v[80:83], v[72:75], v[20:35]
	ds_read_b128 v[80:83], v138
	ds_read_b128 v[76:79], v138 offset:32
	ds_read_b128 v[112:115], v138 offset:64
	ds_read_b128 v[116:119], v138 offset:96
.LBB0_314:
	s_waitcnt lgkmcnt(0)
	v_pk_mul_f32 v[24:25], v[24:25], v[76:77]
	v_lshl_add_u32 v76, v123, 1, 0
	v_pk_mul_f32 v[20:21], v[20:21], v[80:81]
	v_add_u32_e32 v80, 0xe000, v76
	v_pk_mul_f32 v[26:27], v[26:27], v[78:79]
	v_pk_mul_f32 v[22:23], v[22:23], v[82:83]
	ds_read2_b64 v[76:79], v80 offset0:192 offset1:194
	ds_read2_b64 v[80:83], v80 offset0:196 offset1:198
	s_waitcnt lgkmcnt(0)
	v_mfma_f32_32x32x16_bf16 v[4:19], v[76:79], v[68:71], v[4:19]
	v_mul_f32_e64 v34, v34, v118
	v_mul_f32_e64 v35, v35, v119
	v_mul_f32_e64 v30, v30, v114
	v_mul_f32_e64 v31, v31, v115
	v_mul_f32_e64 v32, v32, v116
	v_mul_f32_e64 v33, v33, v117
	v_pk_mul_f32 v[28:29], v[28:29], v[112:113]
	v_mfma_f32_32x32x16_bf16 v[52:67], v[104:107], v[68:71], v[52:67]
	v_lshlrev_b32_e32 v68, 2, v121
	v_lshlrev_b32_e32 v69, 10, v188
	v_add3_u32 v68, s80, v68, v69
	v_mfma_f32_32x32x16_bf16 v[4:19], v[80:83], v[72:75], v[4:19]
	ds_read_b128 v[76:79], v138 offset:128
	ds_read_b128 v[80:83], v138 offset:160
	ds_read_b128 v[112:115], v138 offset:192
	ds_read_b128 v[116:119], v138 offset:224
	v_mfma_f32_32x32x16_bf16 v[52:67], v[108:111], v[72:75], v[52:67]
	s_waitcnt lgkmcnt(0)
	s_nop 5
	v_mul_f32_e64 v18, v18, v118
	v_mul_f32_e64 v19, v19, v119
	v_mul_f32_e64 v16, v16, v116
	v_mul_f32_e64 v17, v17, v117
	v_pk_mul_f32 v[14:15], v[14:15], v[114:115]
	v_pk_mul_f32 v[12:13], v[12:13], v[112:113]
	v_pk_mul_f32 v[10:11], v[10:11], v[82:83]
	v_pk_mul_f32 v[8:9], v[8:9], v[80:81]
	v_pk_mul_f32 v[6:7], v[6:7], v[78:79]
	v_pk_mul_f32 v[4:5], v[4:5], v[76:77]
	ds_write2st64_b32 v68, v52, v53 offset1:1
	ds_write2st64_b32 v68, v54, v55 offset0:2 offset1:3
	ds_write2st64_b32 v68, v56, v57 offset0:8 offset1:9
	ds_write2st64_b32 v68, v58, v59 offset0:10 offset1:11
	ds_write2st64_b32 v68, v60, v61 offset0:16 offset1:17
	ds_write2st64_b32 v68, v62, v63 offset0:18 offset1:19
	ds_write2st64_b32 v68, v64, v65 offset0:24 offset1:25
	ds_write2st64_b32 v68, v66, v67 offset0:26 offset1:27
